# MLA: eight (instead of four) transposed V reads per P.V cluster issued before the row-max reduction; size neutral; on top of v165
# baseline (speedup 1.0000x reference)
.LBB0_360:
	ds_read_b64_tr_b16 v[182:183], v2 offset:53248
	ds_read_b64_tr_b16 v[184:185], v2 offset:53760
	ds_read_b64_tr_b16 v[186:187], v2 offset:54272
	ds_read_b64_tr_b16 v[188:189], v2 offset:54784
	ds_read_b64_tr_b16 v[190:191], v2 offset:57344
	ds_read_b64_tr_b16 v[192:193], v2 offset:57856
	ds_read_b64_tr_b16 v[194:195], v2 offset:58368
	ds_read_b64_tr_b16 v[196:197], v2 offset:58880
	s_nop 2
	v_max3_f32 v0, v81, v97, v82
	v_max3_f32 v0, v0, v98, v80
	v_max3_f32 v0, v0, v96, v83
	v_max3_f32 v0, v0, v99, v84
	v_max3_f32 v0, v0, v100, v85
	v_max3_f32 v0, v0, v101, v86
	v_max3_f32 v0, v0, v102, v87
	v_max3_f32 v0, v0, v103, v88
	v_max3_f32 v0, v0, v104, v89
	v_max3_f32 v0, v0, v105, v90
	v_max3_f32 v0, v0, v106, v91
	v_max3_f32 v0, v0, v107, v92
	v_max3_f32 v0, v0, v108, v93
	v_max3_f32 v0, v0, v109, v94
	v_max3_f32 v0, v0, v110, v95
	v_max_f32_e32 v0, v0, v111
	s_cmp_eq_u32 s57, 0
	s_cselect_b64 s[10:11], -1, 0
	s_cmp_lg_u32 s57, 0
	s_cbranch_scc0 .LBB0_368
	v_cmp_lt_f32_e32 vcc, s85, v0
	s_cmp_lg_u64 vcc, 0
	s_cselect_b64 s[36:37], -1, 0
	s_cbranch_execz .LBB0_369
	s_branch .LBB0_370

.LBB0_365:
	ds_read_b64_tr_b16 v[182:183], v2 offset:61440
	ds_read_b64_tr_b16 v[184:185], v2 offset:61952
	ds_read_b64_tr_b16 v[186:187], v2 offset:62464
	ds_read_b64_tr_b16 v[188:189], v2 offset:62976
	v_add_u32_e32 v198, 0xd000, v2
	ds_read_b64_tr_b16 v[190:191], v198 offset:12288
	ds_read_b64_tr_b16 v[192:193], v198 offset:12800
	ds_read_b64_tr_b16 v[194:195], v198 offset:13312
	ds_read_b64_tr_b16 v[196:197], v198 offset:13824
	s_nop 1
	v_max3_f32 v0, v81, v97, v82
	v_max3_f32 v0, v0, v98, v80
	v_max3_f32 v0, v0, v96, v83
	v_max3_f32 v0, v0, v99, v84
	v_max3_f32 v0, v0, v100, v85
	v_max3_f32 v0, v0, v101, v86
	v_max3_f32 v0, v0, v102, v87
	v_max3_f32 v0, v0, v103, v88
	v_max3_f32 v0, v0, v104, v89
	v_max3_f32 v0, v0, v105, v90
	v_max3_f32 v0, v0, v106, v91
	v_max3_f32 v0, v0, v107, v92
	v_max3_f32 v0, v0, v108, v93
	v_max3_f32 v0, v0, v109, v94
	v_max3_f32 v0, v0, v110, v95
	v_max_f32_e64 v0, v0, v111
	v_cmp_lt_f32_e32 vcc, s85, v0
	s_cbranch_vccz .LBB0_367
	ds_bpermute_b32 v3, v178, v0
	s_waitcnt lgkmcnt(0)
	v_max3_f32 v0, v0, v3, 0
	v_exp_f32_e64 v4, -v0
	v_add_f32_e32 v165, v165, v0
	v_xor_b32_e32 v64, 0x80000000, v165
	v_pk_add_f32 v[80:81], v[80:81], v[0:1] op_sel_hi:[1,0] neg_lo:[0,1] neg_hi:[0,1]
	v_pk_add_f32 v[96:97], v[96:97], v[0:1] op_sel_hi:[1,0] neg_lo:[0,1] neg_hi:[0,1]
	v_pk_add_f32 v[82:83], v[82:83], v[0:1] op_sel_hi:[1,0] neg_lo:[0,1] neg_hi:[0,1]
	v_pk_add_f32 v[98:99], v[98:99], v[0:1] op_sel_hi:[1,0] neg_lo:[0,1] neg_hi:[0,1]
	v_pk_add_f32 v[84:85], v[84:85], v[0:1] op_sel_hi:[1,0] neg_lo:[0,1] neg_hi:[0,1]
	v_pk_add_f32 v[100:101], v[100:101], v[0:1] op_sel_hi:[1,0] neg_lo:[0,1] neg_hi:[0,1]
	v_pk_add_f32 v[86:87], v[86:87], v[0:1] op_sel_hi:[1,0] neg_lo:[0,1] neg_hi:[0,1]
	v_pk_add_f32 v[102:103], v[102:103], v[0:1] op_sel_hi:[1,0] neg_lo:[0,1] neg_hi:[0,1]
	v_pk_add_f32 v[88:89], v[88:89], v[0:1] op_sel_hi:[1,0] neg_lo:[0,1] neg_hi:[0,1]
	v_pk_add_f32 v[104:105], v[104:105], v[0:1] op_sel_hi:[1,0] neg_lo:[0,1] neg_hi:[0,1]
	v_pk_add_f32 v[90:91], v[90:91], v[0:1] op_sel_hi:[1,0] neg_lo:[0,1] neg_hi:[0,1]
	v_pk_add_f32 v[106:107], v[106:107], v[0:1] op_sel_hi:[1,0] neg_lo:[0,1] neg_hi:[0,1]
	v_pk_add_f32 v[92:93], v[92:93], v[0:1] op_sel_hi:[1,0] neg_lo:[0,1] neg_hi:[0,1]
	v_pk_add_f32 v[108:109], v[108:109], v[0:1] op_sel_hi:[1,0] neg_lo:[0,1] neg_hi:[0,1]
	v_pk_add_f32 v[94:95], v[94:95], v[0:1] op_sel_hi:[1,0] neg_lo:[0,1] neg_hi:[0,1]
	v_pk_add_f32 v[110:111], v[110:111], v[0:1] op_sel_hi:[1,0] neg_lo:[0,1] neg_hi:[0,1]
	v_pk_mul_f32 v[62:63], v[62:63], v[4:5] op_sel_hi:[1,0]
	v_pk_mul_f32 v[60:61], v[60:61], v[4:5] op_sel_hi:[1,0]
	v_pk_mul_f32 v[58:59], v[58:59], v[4:5] op_sel_hi:[1,0]
	v_pk_mul_f32 v[56:57], v[56:57], v[4:5] op_sel_hi:[1,0]
	v_pk_mul_f32 v[54:55], v[54:55], v[4:5] op_sel_hi:[1,0]
	v_pk_mul_f32 v[52:53], v[52:53], v[4:5] op_sel_hi:[1,0]
	v_pk_mul_f32 v[50:51], v[50:51], v[4:5] op_sel_hi:[1,0]
	v_pk_mul_f32 v[48:49], v[48:49], v[4:5] op_sel_hi:[1,0]
	v_pk_mul_f32 v[46:47], v[46:47], v[4:5] op_sel_hi:[1,0]
	v_pk_mul_f32 v[44:45], v[44:45], v[4:5] op_sel_hi:[1,0]
	v_pk_mul_f32 v[42:43], v[42:43], v[4:5] op_sel_hi:[1,0]
	v_pk_mul_f32 v[40:41], v[40:41], v[4:5] op_sel_hi:[1,0]
	v_pk_mul_f32 v[38:39], v[38:39], v[4:5] op_sel_hi:[1,0]
	v_pk_mul_f32 v[36:37], v[36:37], v[4:5] op_sel_hi:[1,0]
	v_pk_mul_f32 v[34:35], v[34:35], v[4:5] op_sel_hi:[1,0]
	v_pk_mul_f32 v[32:33], v[32:33], v[4:5] op_sel_hi:[1,0]
	v_mov_b32_e32 v65, v64
	v_mov_b32_e32 v66, v64
	v_mov_b32_e32 v67, v64
	v_mov_b32_e32 v68, v64
	v_mov_b32_e32 v69, v64
	v_mov_b32_e32 v70, v64
	v_mov_b32_e32 v71, v64
	v_mov_b32_e32 v72, v64
	v_mov_b32_e32 v73, v64
	v_mov_b32_e32 v74, v64
	v_mov_b32_e32 v75, v64
	v_mov_b32_e32 v76, v64
	v_mov_b32_e32 v77, v64
	v_mov_b32_e32 v78, v64
	v_mov_b32_e32 v79, v64
	v_mul_f32_e32 v6, v6, v4
.LBB0_367:
	v_exp_f32_e32 v3, v80
	v_exp_f32_e32 v7, v96
	v_exp_f32_e32 v0, v81
	v_exp_f32_e32 v4, v97
	v_exp_f32_e32 v17, v98
	v_add_f32_e32 v5, v7, v3
	v_exp_f32_e32 v14, v99
	v_pk_add_f32 v[8:9], v[4:5], v[0:1]
	v_exp_f32_e32 v5, v82
	v_pk_add_f32 v[10:11], v[8:9], v[8:9] op_sel_hi:[0,1]
	v_exp_f32_e32 v10, v83
	v_exp_f32_e32 v18, v101
	v_add_f32_e32 v15, v17, v5
	v_exp_f32_e32 v22, v103
	v_pk_add_f32 v[8:9], v[14:15], v[10:11]
	v_exp_f32_e32 v11, v84
	v_pk_add_f32 v[12:13], v[8:9], v[8:9] op_sel_hi:[0,1]
	v_exp_f32_e32 v15, v100
	v_exp_f32_e32 v12, v85
	v_exp_f32_e32 v26, v105
	v_exp_f32_e32 v30, v107
	v_add_f32_e32 v19, v15, v11
	v_pk_add_f32 v[8:9], v[18:19], v[12:13]
	v_exp_f32_e32 v13, v86
	v_pk_add_f32 v[20:21], v[8:9], v[8:9] op_sel_hi:[0,1]
	v_exp_f32_e32 v19, v102
	v_exp_f32_e32 v20, v87
	v_exp_f32_e32 v82, v109
	v_add_f32_e32 v23, v19, v13
	v_pk_add_f32 v[8:9], v[22:23], v[20:21]
	v_exp_f32_e32 v21, v88
	v_pk_add_f32 v[24:25], v[8:9], v[8:9] op_sel_hi:[0,1]
	v_exp_f32_e32 v23, v104
	v_exp_f32_e32 v24, v89
	v_add_f32_e32 v27, v23, v21
	v_pk_add_f32 v[8:9], v[26:27], v[24:25]
	v_exp_f32_e32 v25, v90
	v_pk_add_f32 v[28:29], v[8:9], v[8:9] op_sel_hi:[0,1]
	v_exp_f32_e32 v27, v106
	v_exp_f32_e32 v28, v91
	v_exp_f32_e32 v91, v94
	v_exp_f32_e32 v90, v111
	v_add_f32_e32 v31, v27, v25
	v_pk_add_f32 v[8:9], v[30:31], v[28:29]
	v_exp_f32_e32 v29, v92
	v_pk_add_f32 v[80:81], v[8:9], v[8:9] op_sel_hi:[0,1]
	v_exp_f32_e32 v31, v108
	v_exp_f32_e32 v80, v93
	v_exp_f32_e32 v92, v110
	v_add_f32_e32 v83, v31, v29
	v_pk_add_f32 v[8:9], v[82:83], v[80:81]
	s_nop 0
	v_pk_add_f32 v[88:89], v[8:9], v[8:9] op_sel_hi:[0,1]
	v_exp_f32_e32 v88, v95
	v_cvt_pk_bf16_f32 v8, v3, v0
	v_cvt_pk_bf16_f32 v9, v5, v10
	v_cvt_pk_bf16_f32 v10, v11, v12
	v_cvt_pk_bf16_f32 v11, v13, v20
	v_cvt_pk_bf16_f32 v12, v7, v4
	v_cvt_pk_bf16_f32 v13, v17, v14
	v_cvt_pk_bf16_f32 v14, v15, v18
	v_cvt_pk_bf16_f32 v15, v19, v22
	v_cvt_pk_bf16_f32 v18, v21, v24
	v_cvt_pk_bf16_f32 v19, v25, v28
	v_cvt_pk_bf16_f32 v20, v29, v80
	v_cvt_pk_bf16_f32 v21, v91, v88
	v_cvt_pk_bf16_f32 v22, v23, v26
	v_cvt_pk_bf16_f32 v23, v27, v30
	v_cvt_pk_bf16_f32 v24, v31, v82
	v_cvt_pk_bf16_f32 v25, v92, v90
	s_waitcnt lgkmcnt(2)
	v_mfma_f32_32x32x16_bf16 v[48:63], v[182:185], v[8:11], v[48:63]
	v_add_f32_e32 v91, v92, v91
	s_waitcnt lgkmcnt(2)
	v_mfma_f32_32x32x16_bf16 v[32:47], v[190:193], v[8:11], v[32:47]
	v_mfma_f32_32x32x16_bf16 v[48:63], v[186:189], v[18:21], v[48:63]
	s_waitcnt lgkmcnt(0)
	v_mfma_f32_32x32x16_bf16 v[32:47], v[194:197], v[18:21], v[32:47]
	ds_read_b64_tr_b16 v[8:9], v2 offset:63488
	ds_read_b64_tr_b16 v[10:11], v2 offset:64000
	ds_read_b64_tr_b16 v[18:19], v2 offset:64512
	ds_read_b64_tr_b16 v[20:21], v2 offset:65024
	s_waitcnt lgkmcnt(2)
	v_mfma_f32_32x32x16_bf16 v[48:63], v[8:11], v[12:15], v[48:63]
	ds_read_b64_tr_b16 v[2:3], v198 offset:14336
	ds_read_b64_tr_b16 v[4:5], v198 offset:14848
	ds_read_b64_tr_b16 v[8:9], v198 offset:15360
	ds_read_b64_tr_b16 v[10:11], v198 offset:15872
	s_waitcnt lgkmcnt(2)
	v_mfma_f32_32x32x16_bf16 v[32:47], v[2:5], v[12:15], v[32:47]
	v_add_f32_e64 v2, v90, v88
	v_add_f32_e64 v3, v91, v89
	v_add_f32_e32 v0, v2, v3
	v_add_f32_e32 v6, v6, v0
	v_mfma_f32_32x32x16_bf16 v[48:63], v[18:21], v[22:25], v[48:63]
	s_waitcnt lgkmcnt(0)
	v_mfma_f32_32x32x16_bf16 v[32:47], v[8:11], v[22:25], v[32:47]
	s_andn2_b64 vcc, exec, s[4:5]
	s_cbranch_vccnz .LBB0_350
	s_branch .LBB0_374

.LBB0_372:
	v_exp_f32_e32 v7, v80
	v_exp_f32_e32 v17, v96
	v_exp_f32_e32 v0, v81
	v_exp_f32_e32 v4, v97
	v_exp_f32_e32 v96, v98
	v_add_f32_e32 v5, v17, v7
	v_exp_f32_e32 v14, v99
	v_pk_add_f32 v[8:9], v[4:5], v[0:1]
	v_exp_f32_e32 v5, v82
	v_pk_add_f32 v[10:11], v[8:9], v[8:9] op_sel_hi:[0,1]
	v_exp_f32_e32 v10, v83
	v_exp_f32_e32 v18, v101
	v_add_f32_e32 v15, v96, v5
	v_exp_f32_e32 v22, v103
	v_pk_add_f32 v[8:9], v[14:15], v[10:11]
	v_exp_f32_e32 v11, v84
	v_pk_add_f32 v[12:13], v[8:9], v[8:9] op_sel_hi:[0,1]
	v_exp_f32_e32 v15, v100
	v_exp_f32_e32 v12, v85
	v_exp_f32_e32 v26, v105
	v_exp_f32_e32 v30, v107
	v_add_f32_e32 v19, v15, v11
	v_pk_add_f32 v[8:9], v[18:19], v[12:13]
	v_exp_f32_e32 v13, v86
	v_pk_add_f32 v[20:21], v[8:9], v[8:9] op_sel_hi:[0,1]
	v_exp_f32_e32 v19, v102
	v_exp_f32_e32 v20, v87
	v_exp_f32_e32 v82, v109
	v_add_f32_e32 v23, v19, v13
	v_pk_add_f32 v[8:9], v[22:23], v[20:21]
	v_exp_f32_e32 v21, v88
	v_pk_add_f32 v[24:25], v[8:9], v[8:9] op_sel_hi:[0,1]
	v_exp_f32_e32 v23, v104
	v_exp_f32_e32 v24, v89
	v_add_f32_e32 v27, v23, v21
	v_pk_add_f32 v[8:9], v[26:27], v[24:25]
	v_exp_f32_e32 v25, v90
	v_pk_add_f32 v[28:29], v[8:9], v[8:9] op_sel_hi:[0,1]
	v_exp_f32_e32 v27, v106
	v_exp_f32_e32 v28, v91
	v_exp_f32_e32 v91, v94
	v_exp_f32_e32 v90, v111
	v_add_f32_e32 v31, v27, v25
	v_pk_add_f32 v[8:9], v[30:31], v[28:29]
	v_exp_f32_e32 v29, v92
	v_pk_add_f32 v[80:81], v[8:9], v[8:9] op_sel_hi:[0,1]
	v_exp_f32_e32 v31, v108
	v_exp_f32_e32 v80, v93
	v_exp_f32_e32 v92, v110
	v_add_f32_e32 v83, v31, v29
	v_pk_add_f32 v[8:9], v[82:83], v[80:81]
	s_nop 0
	v_pk_add_f32 v[88:89], v[8:9], v[8:9] op_sel_hi:[0,1]
	v_exp_f32_e32 v88, v95
	v_cvt_pk_bf16_f32 v8, v7, v0
	v_cvt_pk_bf16_f32 v9, v5, v10
	v_cvt_pk_bf16_f32 v10, v11, v12
	v_cvt_pk_bf16_f32 v11, v13, v20
	v_cvt_pk_bf16_f32 v12, v17, v4
	v_cvt_pk_bf16_f32 v13, v96, v14
	v_cvt_pk_bf16_f32 v14, v15, v18
	v_cvt_pk_bf16_f32 v15, v19, v22
	v_cvt_pk_bf16_f32 v18, v21, v24
	v_cvt_pk_bf16_f32 v19, v25, v28
	v_cvt_pk_bf16_f32 v20, v29, v80
	v_cvt_pk_bf16_f32 v21, v91, v88
	v_cvt_pk_bf16_f32 v22, v23, v26
	v_cvt_pk_bf16_f32 v23, v27, v30
	v_cvt_pk_bf16_f32 v24, v31, v82
	v_cvt_pk_bf16_f32 v25, v92, v90
	s_waitcnt lgkmcnt(2)
	v_mfma_f32_32x32x16_bf16 v[48:63], v[182:185], v[8:11], v[48:63]
	v_add_f32_e32 v91, v92, v91
	v_pk_add_f32 v[4:5], v[90:91], v[88:89]
	s_nop 0
	v_add_f32_e32 v0, v4, v5
	v_add_f32_e32 v6, v6, v0
	s_waitcnt lgkmcnt(2)
	v_mfma_f32_32x32x16_bf16 v[32:47], v[190:193], v[8:11], v[32:47]
	v_mfma_f32_32x32x16_bf16 v[48:63], v[186:189], v[18:21], v[48:63]
	s_waitcnt lgkmcnt(0)
	v_mfma_f32_32x32x16_bf16 v[32:47], v[194:197], v[18:21], v[32:47]
	ds_read_b64_tr_b16 v[8:9], v2 offset:55296
	ds_read_b64_tr_b16 v[10:11], v2 offset:55808
	ds_read_b64_tr_b16 v[18:19], v2 offset:56320
	ds_read_b64_tr_b16 v[20:21], v2 offset:56832
	s_waitcnt lgkmcnt(2)
	v_mfma_f32_32x32x16_bf16 v[48:63], v[8:11], v[12:15], v[48:63]
	ds_read_b64_tr_b16 v[8:9], v2 offset:59392
	ds_read_b64_tr_b16 v[10:11], v2 offset:59904
	ds_read_b64_tr_b16 v[26:27], v2 offset:60416
	ds_read_b64_tr_b16 v[28:29], v2 offset:60928
	s_waitcnt lgkmcnt(2)
	v_mfma_f32_32x32x16_bf16 v[32:47], v[8:11], v[12:15], v[32:47]
	v_mfma_f32_32x32x16_bf16 v[48:63], v[18:21], v[22:25], v[48:63]
	s_waitcnt lgkmcnt(0)
	v_mfma_f32_32x32x16_bf16 v[32:47], v[26:29], v[22:25], v[32:47]
	s_add_i32 s2, s57, 64
	s_cmp_gt_i32 s2, s54
	s_cbranch_scc0 .LBB0_363

.LBB0_398:
	ds_read_b64_tr_b16 v[182:183], v2 offset:53248
	ds_read_b64_tr_b16 v[184:185], v2 offset:53760
	ds_read_b64_tr_b16 v[186:187], v2 offset:54272
	ds_read_b64_tr_b16 v[188:189], v2 offset:54784
	ds_read_b64_tr_b16 v[190:191], v2 offset:57344
	ds_read_b64_tr_b16 v[192:193], v2 offset:57856
	ds_read_b64_tr_b16 v[194:195], v2 offset:58368
	ds_read_b64_tr_b16 v[196:197], v2 offset:58880
	s_nop 2
	v_max3_f32 v0, v81, v97, v82
	v_max3_f32 v0, v0, v98, v80
	v_max3_f32 v0, v0, v96, v83
	v_max3_f32 v0, v0, v99, v84
	v_max3_f32 v0, v0, v100, v85
	v_max3_f32 v0, v0, v101, v86
	v_max3_f32 v0, v0, v102, v87
	v_max3_f32 v0, v0, v103, v88
	v_max3_f32 v0, v0, v104, v89
	v_max3_f32 v0, v0, v105, v90
	v_max3_f32 v0, v0, v106, v91
	v_max3_f32 v0, v0, v107, v92
	v_max3_f32 v0, v0, v108, v93
	v_max3_f32 v0, v0, v109, v94
	v_max3_f32 v0, v0, v110, v95
	v_max_f32_e32 v0, v0, v111
	s_cmp_eq_u32 s37, 0
	s_cselect_b64 s[10:11], -1, 0
	s_cmp_lg_u32 s37, 0
	s_cbranch_scc0 .LBB0_406
	v_cmp_lt_f32_e32 vcc, s85, v0
	s_cmp_lg_u64 vcc, 0
	s_cselect_b64 s[16:17], -1, 0
	s_cbranch_execz .LBB0_407
	s_branch .LBB0_408

.LBB0_410:
	v_exp_f32_e32 v7, v80
	v_exp_f32_e32 v17, v96
	v_exp_f32_e32 v0, v81
	v_exp_f32_e32 v4, v97
	v_exp_f32_e32 v96, v98
	v_add_f32_e32 v5, v17, v7
	v_exp_f32_e32 v14, v99
	v_pk_add_f32 v[8:9], v[4:5], v[0:1]
	v_exp_f32_e32 v5, v82
	v_pk_add_f32 v[10:11], v[8:9], v[8:9] op_sel_hi:[0,1]
	v_exp_f32_e32 v10, v83
	v_exp_f32_e32 v18, v101
	v_add_f32_e32 v15, v96, v5
	v_exp_f32_e32 v22, v103
	v_pk_add_f32 v[8:9], v[14:15], v[10:11]
	v_exp_f32_e32 v11, v84
	v_pk_add_f32 v[12:13], v[8:9], v[8:9] op_sel_hi:[0,1]
	v_exp_f32_e32 v15, v100
	v_exp_f32_e32 v12, v85
	v_exp_f32_e32 v26, v105
	v_exp_f32_e32 v30, v107
	v_add_f32_e32 v19, v15, v11
	v_pk_add_f32 v[8:9], v[18:19], v[12:13]
	v_exp_f32_e32 v13, v86
	v_pk_add_f32 v[20:21], v[8:9], v[8:9] op_sel_hi:[0,1]
	v_exp_f32_e32 v19, v102
	v_exp_f32_e32 v20, v87
	v_exp_f32_e32 v82, v109
	v_add_f32_e32 v23, v19, v13
	v_pk_add_f32 v[8:9], v[22:23], v[20:21]
	v_exp_f32_e32 v21, v88
	v_pk_add_f32 v[24:25], v[8:9], v[8:9] op_sel_hi:[0,1]
	v_exp_f32_e32 v23, v104
	v_exp_f32_e32 v24, v89
	v_add_f32_e32 v27, v23, v21
	v_pk_add_f32 v[8:9], v[26:27], v[24:25]
	v_exp_f32_e32 v25, v90
	v_pk_add_f32 v[28:29], v[8:9], v[8:9] op_sel_hi:[0,1]
	v_exp_f32_e32 v27, v106
	v_exp_f32_e32 v28, v91
	v_exp_f32_e32 v91, v94
	v_exp_f32_e32 v90, v111
	v_add_f32_e32 v31, v27, v25
	v_pk_add_f32 v[8:9], v[30:31], v[28:29]
	v_exp_f32_e32 v29, v92
	v_pk_add_f32 v[80:81], v[8:9], v[8:9] op_sel_hi:[0,1]
	v_exp_f32_e32 v31, v108
	v_exp_f32_e32 v80, v93
	v_exp_f32_e32 v92, v110
	v_add_f32_e32 v83, v31, v29
	v_pk_add_f32 v[8:9], v[82:83], v[80:81]
	s_nop 0
	v_pk_add_f32 v[88:89], v[8:9], v[8:9] op_sel_hi:[0,1]
	v_exp_f32_e32 v88, v95
	v_cvt_pk_bf16_f32 v8, v7, v0
	v_cvt_pk_bf16_f32 v9, v5, v10
	v_cvt_pk_bf16_f32 v10, v11, v12
	v_cvt_pk_bf16_f32 v11, v13, v20
	v_cvt_pk_bf16_f32 v12, v17, v4
	v_cvt_pk_bf16_f32 v13, v96, v14
	v_cvt_pk_bf16_f32 v14, v15, v18
	v_cvt_pk_bf16_f32 v15, v19, v22
	v_cvt_pk_bf16_f32 v18, v21, v24
	v_cvt_pk_bf16_f32 v19, v25, v28
	v_cvt_pk_bf16_f32 v20, v29, v80
	v_cvt_pk_bf16_f32 v21, v91, v88
	v_cvt_pk_bf16_f32 v22, v23, v26
	v_cvt_pk_bf16_f32 v23, v27, v30
	v_cvt_pk_bf16_f32 v24, v31, v82
	v_cvt_pk_bf16_f32 v25, v92, v90
	s_waitcnt lgkmcnt(2)
	v_mfma_f32_32x32x16_bf16 v[48:63], v[182:185], v[8:11], v[48:63]
	v_add_f32_e32 v91, v92, v91
	v_pk_add_f32 v[4:5], v[90:91], v[88:89]
	s_nop 0
	v_add_f32_e32 v0, v4, v5
	v_add_f32_e32 v6, v6, v0
	s_waitcnt lgkmcnt(2)
	v_mfma_f32_32x32x16_bf16 v[32:47], v[190:193], v[8:11], v[32:47]
	v_mfma_f32_32x32x16_bf16 v[48:63], v[186:189], v[18:21], v[48:63]
	s_waitcnt lgkmcnt(0)
	v_mfma_f32_32x32x16_bf16 v[32:47], v[194:197], v[18:21], v[32:47]
	ds_read_b64_tr_b16 v[8:9], v2 offset:55296
	ds_read_b64_tr_b16 v[10:11], v2 offset:55808
	ds_read_b64_tr_b16 v[18:19], v2 offset:56320
	ds_read_b64_tr_b16 v[20:21], v2 offset:56832
	s_waitcnt lgkmcnt(2)
	v_mfma_f32_32x32x16_bf16 v[48:63], v[8:11], v[12:15], v[48:63]
	ds_read_b64_tr_b16 v[8:9], v2 offset:59392
	ds_read_b64_tr_b16 v[10:11], v2 offset:59904
	ds_read_b64_tr_b16 v[26:27], v2 offset:60416
	ds_read_b64_tr_b16 v[28:29], v2 offset:60928
	s_waitcnt lgkmcnt(2)
	v_mfma_f32_32x32x16_bf16 v[32:47], v[8:11], v[12:15], v[32:47]
	v_mfma_f32_32x32x16_bf16 v[48:63], v[18:21], v[22:25], v[48:63]
	s_waitcnt lgkmcnt(0)
	v_mfma_f32_32x32x16_bf16 v[32:47], v[26:29], v[22:25], v[32:47]
	s_add_i32 s2, s37, 64
	s_cmp_gt_i32 s2, s28
	s_cbranch_scc0 .LBB0_401
